# attention tile loop: static s_setprio 1 for waves 0-3 (the other half), reset after the loop
# speedup vs baseline: 1.0131x; 1.0131x over previous
.LBB0_1098:
	s_xor_b64 s[30:31], s[0:1], -1
	s_and_b64 s[0:1], s[0:1], exec
	s_cselect_b32 s1, s19, s37
	v_mov_b32_e32 v174, v190
	s_lshl_b32 s14, s1, 15
	s_lshl_b32 s0, s1, 16
	s_add_u32 s4, s16, s0
	v_readfirstlane_b32 s7, v174
	s_addc_u32 s5, s17, 0
	s_ashr_i32 s0, s7, 6
	v_lshlrev_b32_e32 v1, 3, v174
	s_lshl_b32 s6, s1, 8
	s_lshl_b32 s38, s1, 2
	s_ashr_i32 s1, s0, 31
	v_ashrrev_i32_e32 v0, 4, v174
	v_and_b32_e32 v2, 0x78, v1
	v_and_b32_e32 v175, 31, v174
	v_bfe_u32 v176, v174, 5, 1
	s_lshl_b32 s39, s0, 5
	s_and_b32 s7, s7, 0x3fffffc0
	s_lshl_b64 s[28:29], s[0:1], 13
	v_lshlrev_b32_e32 v2, 1, v2
	v_lshlrev_b32_e32 v3, 8, v0
	v_lshlrev_b32_e32 v10, 8, v175
	v_lshlrev_b32_e32 v11, 4, v176
	s_add_u32 s0, s4, s28
	v_or_b32_e32 v148, v2, v3
	v_or_b32_e32 v12, v11, v10
	s_addc_u32 s1, s5, s29
	global_load_dwordx4 v[96:99], v148, s[22:23]
	global_load_dwordx4 v[100:103], v148, s[20:21]
	global_load_dwordx4 v[136:139], v148, s[42:43]
	global_load_dwordx4 v[140:143], v148, s[26:27]
	global_load_dwordx4 v[104:107], v12, s[0:1]
	global_load_dwordx4 v[108:111], v12, s[0:1] offset:32
	global_load_dwordx4 v[112:115], v12, s[0:1] offset:64
	global_load_dwordx4 v[116:119], v12, s[0:1] offset:96
	global_load_dwordx4 v[120:123], v12, s[0:1] offset:128
	global_load_dwordx4 v[124:127], v12, s[0:1] offset:160
	global_load_dwordx4 v[128:131], v12, s[0:1] offset:192
	global_load_dwordx4 v[132:135], v12, s[0:1] offset:224
	v_and_b32_e32 v6, 0xfffff0, v0
	v_lshlrev_b32_e32 v7, 1, v0
	v_and_or_b32 v6, v7, 8, v6
	v_lshrrev_b32_e32 v7, 1, v0
	v_and_b32_e32 v8, 3, v0
	v_add_u32_e32 v0, 32, v0
	v_and_b32_e32 v4, 63, v174
	v_and_b32_e32 v9, 0xfffff0, v0
	v_lshlrev_b32_e32 v0, 1, v0
	v_lshlrev_b32_e32 v12, 4, v174
	s_lshl_b32 s0, s7, 2
	v_and_or_b32 v0, v0, 8, v9
	v_lshlrev_b32_e32 v9, 3, v4
	v_and_b32_e32 v13, 0xc0, v12
	v_lshlrev_b32_e32 v14, 1, v174
	s_add_i32 s0, s0, 0
	v_lshlrev_b32_e32 v5, 2, v176
	v_and_or_b32 v13, v9, 24, v13
	v_and_b32_e32 v14, 32, v14
	v_and_b32_e32 v9, 0x100, v9
	s_add_i32 s18, s38, 4
	s_add_i32 s39, s39, s6
	s_add_i32 s4, s0, 0x10000
	v_lshrrev_b32_e32 v6, 1, v6
	v_bfe_u32 v1, v1, 5, 2
	v_lshrrev_b32_e32 v0, 1, v0
	v_or3_b32 v9, v13, v14, v9
	v_subrev_u32_e32 v13, s6, v5
	s_cmp_lg_u32 0, -1
	v_or_b32_e32 v6, v6, v1
	v_and_or_b32 v7, v7, 4, v8
	v_or_b32_e32 v0, v0, v1
	v_and_b32_e32 v1, 0x70, v174
	v_cvt_f32_i32_e32 v13, v13
	s_cselect_b32 s0, 0, 0
	v_lshlrev_b32_e32 v6, 9, v6
	v_lshlrev_b32_e32 v7, 6, v7
	v_and_b32_e32 v8, 48, v2
	v_lshlrev_b32_e32 v0, 9, v0
	v_bitop3_b32 v1, v2, v3, v1 bitop3:0xde
	v_add_u32_e32 v178, s0, v9
	s_movk_i32 s0, 0x70
	v_or3_b32 v0, v0, v7, v8
	v_or3_b32 v6, v6, v7, v8
	v_add_u32_e32 v182, 0, v1
	v_bfe_u32 v200, v174, 7, 1
	v_lshlrev_b32_e32 v200, 7, v200
	v_xor_b32_e32 v182, v182, v200
	v_and_b32_e32 v1, 0x70, v12
	v_bitop3_b32 v2, v11, v12, s0 bitop3:0x78
	s_movk_i32 s0, 0x60
	s_waitcnt vmcnt(0)
	v_add_u32_e32 v180, 0, v6
	v_add_u32_e32 v181, 0, v0
	v_add_u32_e32 v0, 0, v10
	v_bitop3_b32 v3, v11, v1, 32 bitop3:0x36
	v_bitop3_b32 v6, v11, v1, 64 bitop3:0x36
	v_bitop3_b32 v1, v11, v1, s0 bitop3:0x36
	v_cmp_gt_u32_e64 s[0:1], 32, v4
	v_or_b32_e32 v4, s39, v175
	v_mov_b32_e32 v32, v149
	v_mov_b32_e32 v33, v149
	v_mov_b32_e32 v46, v149
	v_mov_b32_e32 v47, v149
	v_mul_f32_e32 v179, v172, v13
	v_add_u32_e32 v177, s4, v11
	v_sub_u32_e32 v184, v4, v5
	v_mov_b32_e32 v34, v149
	v_mov_b32_e32 v35, v149
	v_mov_b32_e32 v36, v149
	v_mov_b32_e32 v37, v149
	v_mov_b32_e32 v38, v149
	v_mov_b32_e32 v39, v149
	v_mov_b32_e32 v40, v149
	v_mov_b32_e32 v41, v149
	v_mov_b32_e32 v42, v149
	v_mov_b32_e32 v43, v149
	v_mov_b32_e32 v44, v149
	v_mov_b32_e32 v45, v149
	v_add_u32_e32 v186, v0, v2
	v_add_u32_e32 v187, v0, v3
	v_add_u32_e32 v188, v0, v6
	v_add_u32_e32 v189, v0, v1
	v_bfe_u32 v200, v174, 3, 1
	v_lshlrev_b32_e32 v200, 7, v200
	v_xor_b32_e32 v186, v186, v200
	v_xor_b32_e32 v187, v187, v200
	v_xor_b32_e32 v188, v188, v200
	v_xor_b32_e32 v189, v189, v200
	v_mov_b64_e32 v[62:63], v[46:47]
	v_mov_b64_e32 v[16:17], v[32:33]
	v_mov_b64_e32 v[0:1], v[32:33]
	s_mov_b32 s12, 0
	v_lshl_add_u32 v183, v175, 2, s4
	v_mov_b32_e32 v203, 0xf149f2ca
	v_mov_b32_e32 v185, 0
	s_movk_i32 s13, 0x7f
	s_mov_b64 s[46:47], s[2:3]
	s_mov_b64 s[40:41], s[24:25]
	v_mov_b64_e32 v[60:61], v[44:45]
	v_mov_b64_e32 v[58:59], v[42:43]
	v_mov_b64_e32 v[56:57], v[40:41]
	v_mov_b64_e32 v[54:55], v[38:39]
	v_mov_b64_e32 v[52:53], v[36:37]
	v_mov_b64_e32 v[50:51], v[34:35]
	v_mov_b64_e32 v[48:49], v[32:33]
	v_mov_b64_e32 v[18:19], v[34:35]
	v_mov_b64_e32 v[20:21], v[36:37]
	v_mov_b64_e32 v[22:23], v[38:39]
	v_mov_b64_e32 v[24:25], v[40:41]
	v_mov_b64_e32 v[26:27], v[42:43]
	v_mov_b64_e32 v[28:29], v[44:45]
	v_mov_b64_e32 v[30:31], v[46:47]
	v_mov_b64_e32 v[2:3], v[34:35]
	v_mov_b64_e32 v[4:5], v[36:37]
	v_mov_b64_e32 v[6:7], v[38:39]
	v_mov_b64_e32 v[8:9], v[40:41]
	v_mov_b64_e32 v[10:11], v[42:43]
	v_mov_b64_e32 v[12:13], v[44:45]
	v_mov_b64_e32 v[14:15], v[46:47]
	s_waitcnt vmcnt(11)
	ds_write_b128 v180, v[96:99]
	s_waitcnt vmcnt(10)
	ds_write_b128 v181, v[100:103]
	s_waitcnt vmcnt(9)
	ds_write_b128 v182, v[136:139] offset:32768
	s_waitcnt vmcnt(8)
	ds_write_b128 v182, v[140:143] offset:40960
	s_waitcnt lgkmcnt(0)
	s_barrier
	v_add_u32_e32 v168, 0x4000, v148
	global_load_dwordx4 v[136:139], v168, s[42:43]
	global_load_dwordx4 v[140:143], v168, s[26:27]
	v_add_u32_e32 v169, 0x4000, v168
	s_mov_b32 s13, 0
	s_mov_b32 s12, 0
	s_mov_b32 s10, 0x3e0293ee
	s_mov_b32 s6, 0x11000
	s_mov_b32 s7, 0
	s_mov_b32 s8, 0x4000
	ds_read_b128 v[236:239], v186 offset:32768
	ds_read_b128 v[240:243], v186 offset:40960
	v_mov_b32_e32 v244, 0
	v_mov_b32_e32 v245, 0
	v_mov_b32_e32 v246, 0
	v_mov_b32_e32 v247, 0
	v_add_u32_e32 v200, s6, v180
	v_add_u32_e32 v201, s6, v181
	ds_write_b128 v200, v[244:247]
	ds_write_b128 v201, v[244:247]
	v_mov_b32_e32 v204, 0
	v_mov_b32_e32 v205, 0
	v_mov_b32_e32 v206, 0
	v_mov_b32_e32 v207, 0
	v_mov_b32_e32 v208, 0
	v_mov_b32_e32 v209, 0
	v_mov_b32_e32 v210, 0
	v_mov_b32_e32 v211, 0
	v_mov_b32_e32 v212, 0
	v_mov_b32_e32 v213, 0
	v_mov_b32_e32 v214, 0
	v_mov_b32_e32 v215, 0
	v_mov_b32_e32 v216, 0
	v_mov_b32_e32 v217, 0
	v_mov_b32_e32 v218, 0
	v_mov_b32_e32 v219, 0
	v_cvt_f32_u32_e32 v64, s13
	v_mov_b32_e32 v165, v164
	v_fma_f32 v64, v172, v64, v179
	v_add_f32_e32 v68, v173, v64
	v_add_f32_e32 v72, v173, v68
	v_add_f32_e32 v76, v173, v72
	v_add_f32_e32 v65, v172, v64
	v_add_f32_e32 v69, v172, v68
	v_add_f32_e32 v73, v172, v72
	v_add_f32_e32 v77, v172, v76
	v_pk_add_f32 v[66:67], v[162:163], v[64:65] op_sel_hi:[1,0]
	v_pk_add_f32 v[70:71], v[162:163], v[68:69] op_sel_hi:[1,0]
	v_pk_add_f32 v[74:75], v[162:163], v[72:73] op_sel_hi:[1,0]
	v_pk_add_f32 v[78:79], v[162:163], v[76:77] op_sel_hi:[1,0]
	v_pk_add_f32 v[82:83], v[164:165], v[66:67]
	v_pk_add_f32 v[80:81], v[166:167], v[64:65]
	v_pk_add_f32 v[86:87], v[164:165], v[70:71]
	v_pk_add_f32 v[84:85], v[164:165], v[68:69]
	v_pk_add_f32 v[90:91], v[164:165], v[74:75]
	v_pk_add_f32 v[88:89], v[164:165], v[72:73]
	v_pk_add_f32 v[94:95], v[164:165], v[78:79]
	v_pk_add_f32 v[92:93], v[164:165], v[76:77]
	s_addk_i32 s13, 0x40
	s_waitcnt lgkmcnt(3)
	v_mfma_f32_32x32x16_bf16 v[64:79], v[236:239], v[104:107], v[64:79]
	ds_read_b128 v[236:239], v187 offset:32768
	s_waitcnt lgkmcnt(3)
	v_mfma_f32_32x32x16_bf16 v[80:95], v[240:243], v[104:107], v[80:95]
	ds_read_b128 v[240:243], v187 offset:40960
	s_waitcnt lgkmcnt(1)
	v_mfma_f32_32x32x16_bf16 v[64:79], v[236:239], v[108:111], v[64:79]
	ds_read_b128 v[236:239], v188 offset:32768
	s_waitcnt lgkmcnt(1)
	v_mfma_f32_32x32x16_bf16 v[80:95], v[240:243], v[108:111], v[80:95]
	ds_read_b128 v[240:243], v188 offset:40960
	s_waitcnt lgkmcnt(1)
	v_mfma_f32_32x32x16_bf16 v[64:79], v[236:239], v[112:115], v[64:79]
	ds_read_b128 v[236:239], v189 offset:32768
	s_waitcnt lgkmcnt(1)
	v_mfma_f32_32x32x16_bf16 v[80:95], v[240:243], v[112:115], v[80:95]
	ds_read_b128 v[240:243], v189 offset:40960
	s_waitcnt lgkmcnt(1)
	v_mfma_f32_32x32x16_bf16 v[64:79], v[236:239], v[116:119], v[64:79]
	v_xor_b32_e32 v186, 0x80, v186
	v_xor_b32_e32 v187, 0x80, v187
	v_xor_b32_e32 v188, 0x80, v188
	v_xor_b32_e32 v189, 0x80, v189
	ds_read_b128 v[236:239], v186 offset:32768
	s_waitcnt lgkmcnt(1)
	v_mfma_f32_32x32x16_bf16 v[80:95], v[240:243], v[116:119], v[80:95]
	ds_read_b128 v[240:243], v186 offset:40960
	s_waitcnt lgkmcnt(1)
	v_mfma_f32_32x32x16_bf16 v[64:79], v[236:239], v[120:123], v[64:79]
	ds_read_b128 v[236:239], v187 offset:32768
	s_waitcnt lgkmcnt(1)
	v_mfma_f32_32x32x16_bf16 v[80:95], v[240:243], v[120:123], v[80:95]
	ds_read_b128 v[240:243], v187 offset:40960
	s_waitcnt lgkmcnt(1)
	v_mfma_f32_32x32x16_bf16 v[64:79], v[236:239], v[124:127], v[64:79]
	ds_read_b128 v[236:239], v188 offset:32768
	s_waitcnt lgkmcnt(1)
	v_mfma_f32_32x32x16_bf16 v[80:95], v[240:243], v[124:127], v[80:95]
	ds_read_b128 v[240:243], v188 offset:40960
	s_waitcnt lgkmcnt(1)
	v_mfma_f32_32x32x16_bf16 v[64:79], v[236:239], v[128:131], v[64:79]
	ds_read_b128 v[236:239], v189 offset:32768
	s_waitcnt lgkmcnt(1)
	v_mfma_f32_32x32x16_bf16 v[80:95], v[240:243], v[128:131], v[80:95]
	ds_read_b128 v[240:243], v189 offset:40960
	s_waitcnt lgkmcnt(1)
	v_mfma_f32_32x32x16_bf16 v[64:79], v[236:239], v[132:135], v[64:79]
	s_waitcnt lgkmcnt(0)
	v_mfma_f32_32x32x16_bf16 v[80:95], v[240:243], v[132:135], v[80:95]
	s_waitcnt vmcnt(0)
	ds_write_b128 v182, v[136:139] offset:49152
	ds_write_b128 v182, v[140:143] offset:57344
	s_waitcnt lgkmcnt(0)
	s_barrier
	v_readfirstlane_b32 s4, v190
	s_nop 3
	s_lshr_b32 s4, s4, 6
	s_cmp_lt_u32 s4, 4
	s_cbranch_scc0 .Lat_prio
	s_setprio 1
